# hand-written unit-edge activation fix-up (all loads in flight) ahead of the down GEMM; barrier: non-leaders poll the top counter
# speedup vs baseline: 1.1482x; 1.0014x over previous
.Ldn_tile:
	s_and_b32 s0, s78, 3
	s_or_b32 s0, s0, s77
	s_cmp_lt_u32 s0, 16
	s_cbranch_scc1 .Ldn_afdone
	s_and_b32 s12, s0, 3
	v_lshrrev_b32_e32 v142, 6, v1
	s_nop 0
	v_readfirstlane_b32 s13, v142
	v_lshlrev_b32_e32 v130, 2, v1
	v_add_u32_e32 v131, 0x800, v130
	v_add_u32_e32 v132, 0x1000, v130
	v_add_u32_e32 v133, 0x1800, v130
	v_add_u32_e32 v134, 0x2000, v130
	v_add_u32_e32 v135, 0x2800, v130
	v_lshlrev_b32_e32 v136, 1, v1
	v_add_u32_e32 v137, 0x400, v136
	v_add_u32_e32 v138, 0x800, v136
	v_add_u32_e32 v139, 0xc00, v136
	v_add_u32_e32 v140, 0x1000, v136
	v_add_u32_e32 v141, 0x1400, v136
	s_mul_i32 s2, s82, 0x8400
	s_add_u32 s16, s38, s2
	s_addc_u32 s17, s39, 0
	s_cmp_eq_u32 s12, 0
	s_cbranch_scc1 .Ldn_afl
	s_mul_i32 s2, s0, 0x5800
	s_add_u32 s14, s6, s2
	s_addc_u32 s15, s7, 0
	s_nop 0
	global_load_dword v66, v130, s[14:15]
	global_load_dword v70, v131, s[14:15]
	global_load_dword v74, v132, s[14:15]
	global_load_dword v78, v133, s[14:15]
	global_load_dword v82, v134, s[14:15]
	s_cmp_gt_u32 s13, 3
	s_cbranch_scc1 .Ldn_af66a
	global_load_dword v86, v135, s[14:15]
.Ldn_af66a:
	s_add_u32 s14, s14, 0xb0000
	s_addc_u32 s15, s15, 0
	s_nop 0
	global_load_dword v69, v130, s[14:15]
	global_load_dword v73, v131, s[14:15]
	global_load_dword v77, v132, s[14:15]
	global_load_dword v81, v133, s[14:15]
	global_load_dword v85, v134, s[14:15]
	s_cmp_gt_u32 s13, 3
	s_cbranch_scc1 .Ldn_af66b
	global_load_dword v89, v135, s[14:15]
.Ldn_af66b:
	s_lshl_b32 s2, s0, 1
	s_add_i32 s2, s2, -1
	s_mul_i32 s2, s2, 0x2c00
	s_add_u32 s2, s2, 0x160000
	s_add_u32 s14, s6, s2
	s_addc_u32 s15, s7, 0
	s_nop 0
	global_load_dword v68, v130, s[14:15]
	global_load_dword v72, v131, s[14:15]
	global_load_dword v76, v132, s[14:15]
	global_load_dword v80, v133, s[14:15]
	global_load_dword v84, v134, s[14:15]
	s_cmp_gt_u32 s13, 3
	s_cbranch_scc1 .Ldn_af66c
	global_load_dword v88, v135, s[14:15]
.Ldn_af66c:
	s_add_u32 s14, s16, 0x0
	s_addc_u32 s15, s17, 0
	s_nop 0
	global_load_dword v67, v130, s[14:15]
	global_load_dword v71, v131, s[14:15]
	global_load_dword v75, v132, s[14:15]
	global_load_dword v79, v133, s[14:15]
	global_load_dword v83, v134, s[14:15]
	s_cmp_gt_u32 s13, 3
	s_cbranch_scc1 .Ldn_af66d
	global_load_dword v87, v135, s[14:15]
.Ldn_af66d:
.Ldn_afl:
	s_cmp_eq_u32 s12, 3
	s_cbranch_scc1 .Ldn_afw
	s_lshl_b32 s2, s0, 1
	s_add_i32 s2, s2, 1
	s_mul_i32 s2, s2, 0x2c00
	s_add_u32 s14, s6, s2
	s_addc_u32 s15, s7, 0
	s_nop 0
	global_load_dword v90, v130, s[14:15]
	global_load_dword v94, v131, s[14:15]
	global_load_dword v98, v132, s[14:15]
	global_load_dword v102, v133, s[14:15]
	global_load_dword v106, v134, s[14:15]
	s_cmp_gt_u32 s13, 3
	s_cbranch_scc1 .Ldn_af90a
	global_load_dword v110, v135, s[14:15]
.Ldn_af90a:
	s_add_u32 s14, s14, 0xb0000
	s_addc_u32 s15, s15, 0
	s_nop 0
	global_load_dword v93, v130, s[14:15]
	global_load_dword v97, v131, s[14:15]
	global_load_dword v101, v132, s[14:15]
	global_load_dword v105, v133, s[14:15]
	global_load_dword v109, v134, s[14:15]
	s_cmp_gt_u32 s13, 3
	s_cbranch_scc1 .Ldn_af90b
	global_load_dword v113, v135, s[14:15]
.Ldn_af90b:
	s_add_i32 s2, s0, 1
	s_mul_i32 s2, s2, 0x5800
	s_add_u32 s2, s2, 0x160000
	s_add_u32 s14, s6, s2
	s_addc_u32 s15, s7, 0
	s_nop 0
	global_load_dword v92, v130, s[14:15]
	global_load_dword v96, v131, s[14:15]
	global_load_dword v100, v132, s[14:15]
	global_load_dword v104, v133, s[14:15]
	global_load_dword v108, v134, s[14:15]
	s_cmp_gt_u32 s13, 3
	s_cbranch_scc1 .Ldn_af90c
	global_load_dword v112, v135, s[14:15]
.Ldn_af90c:
	s_add_u32 s14, s16, 0x5800
	s_addc_u32 s15, s17, 0
	s_nop 0
	global_load_dword v91, v130, s[14:15]
	global_load_dword v95, v131, s[14:15]
	global_load_dword v99, v132, s[14:15]
	global_load_dword v103, v133, s[14:15]
	global_load_dword v107, v134, s[14:15]
	s_cmp_gt_u32 s13, 3
	s_cbranch_scc1 .Ldn_af90d
	global_load_dword v111, v135, s[14:15]
.Ldn_af90d:
.Ldn_afw:
	s_waitcnt vmcnt(0)
	s_cmp_eq_u32 s12, 0
	s_cbranch_scc1 .Ldn_afl2
	s_mul_i32 s2, s0, 0x160000
	s_add_u32 s14, s98, s2
	s_addc_u32 s15, s99, 0
	s_nop 0
	v_fmac_f32_e32 v66, v67, v68
	v_mul_f32_e32 v67, 0x3d922279, v66
	v_fmaak_f32 v67, v66, v67, 0x3fcc422a
	v_mul_f32_e32 v67, v66, v67
	v_mul_f32_e32 v67, 0xbfb8aa3b, v67
	v_exp_f32_e32 v67, v67
	s_nop 0
	v_add_f32_e32 v67, 1.0, v67
	v_rcp_f32_e32 v67, v67
	s_nop 0
	v_mul_f32_e32 v66, v66, v67
	v_mul_f32_e32 v66, v69, v66
	v_cvt_pk_bf16_f32 v66, v66, v66
	global_store_short v136, v66, s[14:15]
	v_fmac_f32_e32 v70, v71, v72
	v_mul_f32_e32 v71, 0x3d922279, v70
	v_fmaak_f32 v71, v70, v71, 0x3fcc422a
	v_mul_f32_e32 v71, v70, v71
	v_mul_f32_e32 v71, 0xbfb8aa3b, v71
	v_exp_f32_e32 v71, v71
	s_nop 0
	v_add_f32_e32 v71, 1.0, v71
	v_rcp_f32_e32 v71, v71
	s_nop 0
	v_mul_f32_e32 v70, v70, v71
	v_mul_f32_e32 v70, v73, v70
	v_cvt_pk_bf16_f32 v70, v70, v70
	global_store_short v137, v70, s[14:15]
	v_fmac_f32_e32 v74, v75, v76
	v_mul_f32_e32 v75, 0x3d922279, v74
	v_fmaak_f32 v75, v74, v75, 0x3fcc422a
	v_mul_f32_e32 v75, v74, v75
	v_mul_f32_e32 v75, 0xbfb8aa3b, v75
	v_exp_f32_e32 v75, v75
	s_nop 0
	v_add_f32_e32 v75, 1.0, v75
	v_rcp_f32_e32 v75, v75
	s_nop 0
	v_mul_f32_e32 v74, v74, v75
	v_mul_f32_e32 v74, v77, v74
	v_cvt_pk_bf16_f32 v74, v74, v74
	global_store_short v138, v74, s[14:15]
	v_fmac_f32_e32 v78, v79, v80
	v_mul_f32_e32 v79, 0x3d922279, v78
	v_fmaak_f32 v79, v78, v79, 0x3fcc422a
	v_mul_f32_e32 v79, v78, v79
	v_mul_f32_e32 v79, 0xbfb8aa3b, v79
	v_exp_f32_e32 v79, v79
	s_nop 0
	v_add_f32_e32 v79, 1.0, v79
	v_rcp_f32_e32 v79, v79
	s_nop 0
	v_mul_f32_e32 v78, v78, v79
	v_mul_f32_e32 v78, v81, v78
	v_cvt_pk_bf16_f32 v78, v78, v78
	global_store_short v139, v78, s[14:15]
	v_fmac_f32_e32 v82, v83, v84
	v_mul_f32_e32 v83, 0x3d922279, v82
	v_fmaak_f32 v83, v82, v83, 0x3fcc422a
	v_mul_f32_e32 v83, v82, v83
	v_mul_f32_e32 v83, 0xbfb8aa3b, v83
	v_exp_f32_e32 v83, v83
	s_nop 0
	v_add_f32_e32 v83, 1.0, v83
	v_rcp_f32_e32 v83, v83
	s_nop 0
	v_mul_f32_e32 v82, v82, v83
	v_mul_f32_e32 v82, v85, v82
	v_cvt_pk_bf16_f32 v82, v82, v82
	global_store_short v140, v82, s[14:15]
	s_cmp_gt_u32 s13, 3
	s_cbranch_scc1 .Ldn_af66e
	v_fmac_f32_e32 v86, v87, v88
	v_mul_f32_e32 v87, 0x3d922279, v86
	v_fmaak_f32 v87, v86, v87, 0x3fcc422a
	v_mul_f32_e32 v87, v86, v87
	v_mul_f32_e32 v87, 0xbfb8aa3b, v87
	v_exp_f32_e32 v87, v87
	s_nop 0
	v_add_f32_e32 v87, 1.0, v87
	v_rcp_f32_e32 v87, v87
	s_nop 0
	v_mul_f32_e32 v86, v86, v87
	v_mul_f32_e32 v86, v89, v86
	v_cvt_pk_bf16_f32 v86, v86, v86
	global_store_short v141, v86, s[14:15]
.Ldn_af66e:
.Ldn_afl2:
	s_cmp_eq_u32 s12, 3
	s_cbranch_scc1 .Ldn_afend
	s_mul_i32 s2, s0, 0x160000
	s_add_u32 s2, s2, 0x15ea00
	s_add_u32 s14, s98, s2
	s_addc_u32 s15, s99, 0
	s_nop 0
	v_fmac_f32_e32 v90, v91, v92
	v_mul_f32_e32 v91, 0x3d922279, v90
	v_fmaak_f32 v91, v90, v91, 0x3fcc422a
	v_mul_f32_e32 v91, v90, v91
	v_mul_f32_e32 v91, 0xbfb8aa3b, v91
	v_exp_f32_e32 v91, v91
	s_nop 0
	v_add_f32_e32 v91, 1.0, v91
	v_rcp_f32_e32 v91, v91
	s_nop 0
	v_mul_f32_e32 v90, v90, v91
	v_mul_f32_e32 v90, v93, v90
	v_cvt_pk_bf16_f32 v90, v90, v90
	global_store_short v136, v90, s[14:15]
	v_fmac_f32_e32 v94, v95, v96
	v_mul_f32_e32 v95, 0x3d922279, v94
	v_fmaak_f32 v95, v94, v95, 0x3fcc422a
	v_mul_f32_e32 v95, v94, v95
	v_mul_f32_e32 v95, 0xbfb8aa3b, v95
	v_exp_f32_e32 v95, v95
	s_nop 0
	v_add_f32_e32 v95, 1.0, v95
	v_rcp_f32_e32 v95, v95
	s_nop 0
	v_mul_f32_e32 v94, v94, v95
	v_mul_f32_e32 v94, v97, v94
	v_cvt_pk_bf16_f32 v94, v94, v94
	global_store_short v137, v94, s[14:15]
	v_fmac_f32_e32 v98, v99, v100
	v_mul_f32_e32 v99, 0x3d922279, v98
	v_fmaak_f32 v99, v98, v99, 0x3fcc422a
	v_mul_f32_e32 v99, v98, v99
	v_mul_f32_e32 v99, 0xbfb8aa3b, v99
	v_exp_f32_e32 v99, v99
	s_nop 0
	v_add_f32_e32 v99, 1.0, v99
	v_rcp_f32_e32 v99, v99
	s_nop 0
	v_mul_f32_e32 v98, v98, v99
	v_mul_f32_e32 v98, v101, v98
	v_cvt_pk_bf16_f32 v98, v98, v98
	global_store_short v138, v98, s[14:15]
	v_fmac_f32_e32 v102, v103, v104
	v_mul_f32_e32 v103, 0x3d922279, v102
	v_fmaak_f32 v103, v102, v103, 0x3fcc422a
	v_mul_f32_e32 v103, v102, v103
	v_mul_f32_e32 v103, 0xbfb8aa3b, v103
	v_exp_f32_e32 v103, v103
	s_nop 0
	v_add_f32_e32 v103, 1.0, v103
	v_rcp_f32_e32 v103, v103
	s_nop 0
	v_mul_f32_e32 v102, v102, v103
	v_mul_f32_e32 v102, v105, v102
	v_cvt_pk_bf16_f32 v102, v102, v102
	global_store_short v139, v102, s[14:15]
	v_fmac_f32_e32 v106, v107, v108
	v_mul_f32_e32 v107, 0x3d922279, v106
	v_fmaak_f32 v107, v106, v107, 0x3fcc422a
	v_mul_f32_e32 v107, v106, v107
	v_mul_f32_e32 v107, 0xbfb8aa3b, v107
	v_exp_f32_e32 v107, v107
	s_nop 0
	v_add_f32_e32 v107, 1.0, v107
	v_rcp_f32_e32 v107, v107
	s_nop 0
	v_mul_f32_e32 v106, v106, v107
	v_mul_f32_e32 v106, v109, v106
	v_cvt_pk_bf16_f32 v106, v106, v106
	global_store_short v140, v106, s[14:15]
	s_cmp_gt_u32 s13, 3
	s_cbranch_scc1 .Ldn_af90e
	v_fmac_f32_e32 v110, v111, v112
	v_mul_f32_e32 v111, 0x3d922279, v110
	v_fmaak_f32 v111, v110, v111, 0x3fcc422a
	v_mul_f32_e32 v111, v110, v111
	v_mul_f32_e32 v111, 0xbfb8aa3b, v111
	v_exp_f32_e32 v111, v111
	s_nop 0
	v_add_f32_e32 v111, 1.0, v111
	v_rcp_f32_e32 v111, v111
	s_nop 0
	v_mul_f32_e32 v110, v110, v111
	v_mul_f32_e32 v110, v113, v110
	v_cvt_pk_bf16_f32 v110, v110, v110
	global_store_short v141, v110, s[14:15]
.Ldn_af90e:
.Ldn_afend:
	s_waitcnt vmcnt(0)
.Ldn_afdone:
	s_barrier
	s_lshr_b32 s1, s78, 2
	s_lshl_b32 s1, s1, 7
	s_lshl_b32 s2, s0, 8
	s_mul_i32 s3, s2, 0x1600
	s_add_u32 s68, s18, s3
	s_addc_u32 s69, s19, 0
	s_mul_i32 s3, s1, 0x1600
	s_add_u32 s70, s80, s3
	s_addc_u32 s71, s81, 0
	s_lshl_b32 s3, s2, 11
	s_lshl_b32 s12, s1, 1
	s_add_u32 s3, s3, s12
	s_add_u32 s74, s24, s3
	s_addc_u32 s75, s25, 0
	s_add_i32 s12, s0, -12
	s_lshr_b32 s12, s12, 2
	s_cmp_lt_u32 s0, 16
	s_cselect_b32 s12, 0, s12
	s_cselect_b32 s14, s52, s54
	s_cselect_b32 s15, s53, s55
	s_mul_i32 s13, s82, 5
	s_add_i32 s12, s12, s13
	s_mul_i32 s12, s12, 0x6000
	s_add_u32 s12, s12, 0x5000
	s_lshl_b32 s13, s1, 2
	s_add_u32 s12, s12, s13
	s_add_u32 s72, s30, s12
	s_addc_u32 s73, s31, 0
	s_and_b32 s12, s0, 15
	s_lshl_b32 s12, s12, 20
	s_add_u32 s12, s12, s13
	s_add_u32 s14, s14, s12
	s_addc_u32 s15, s15, 0
	s_add_u32 m0, s76, 0x0
	s_nop 0
	global_load_lds_dwordx4 v196, s[68:69]
	s_add_u32 m0, s76, 0x2000
	s_nop 0
	global_load_lds_dwordx4 v197, s[68:69]
	s_add_u32 m0, s76, 0x4000
	s_nop 0
	global_load_lds_dwordx4 v198, s[68:69]
	s_add_u32 m0, s76, 0x6000
	s_nop 0
	global_load_lds_dwordx4 v199, s[68:69]
	s_add_u32 m0, s76, 0x8000
	s_nop 0
	global_load_lds_dwordx4 v196, s[70:71]
	s_add_u32 m0, s76, 0xa000
	s_nop 0
	global_load_lds_dwordx4 v197, s[70:71]
	s_add_u32 s68, s68, 0x80
	s_addc_u32 s69, s69, 0
	s_add_u32 s70, s70, 0x80
	s_addc_u32 s71, s71, 0
	s_add_u32 m0, s76, 0xc000
	s_nop 0
	global_load_lds_dwordx4 v196, s[68:69]
	s_add_u32 m0, s76, 0xe000
	s_nop 0
	global_load_lds_dwordx4 v197, s[68:69]
	s_add_u32 m0, s76, 0x10000
	s_nop 0
	global_load_lds_dwordx4 v198, s[68:69]
	s_add_u32 m0, s76, 0x12000
	s_nop 0
	global_load_lds_dwordx4 v199, s[68:69]
	s_add_u32 m0, s76, 0x14000
	s_nop 0
	global_load_lds_dwordx4 v196, s[70:71]
	s_add_u32 m0, s76, 0x16000
	s_nop 0
	global_load_lds_dwordx4 v197, s[70:71]
	s_add_u32 s68, s68, 0x80
	s_addc_u32 s69, s69, 0
	s_add_u32 s70, s70, 0x80
	s_addc_u32 s71, s71, 0
	s_waitcnt vmcnt(6)
	s_waitcnt lgkmcnt(0)
	s_barrier
	v_add_u32_e32 v204, 0x0, v200
	v_add_u32_e32 v205, 0x0, v202
	ds_read_b128 v[130:133], v204 offset:0
	ds_read_b128 v[134:137], v204 offset:2048
	ds_read_b128 v[138:141], v204 offset:4096
	ds_read_b128 v[142:145], v204 offset:6144
	ds_read_b128 v[146:149], v205 offset:0
	ds_read_b128 v[150:153], v205 offset:2048
	ds_read_b128 v[154:157], v205 offset:4096
	ds_read_b128 v[158:161], v205 offset:6144
	s_add_u32 m0, s76, 0x18000
	s_nop 0
	global_load_lds_dwordx4 v196, s[68:69]
	s_add_u32 m0, s76, 0x1a000
	s_nop 0
	global_load_lds_dwordx4 v197, s[68:69]
	s_add_u32 m0, s76, 0x1c000
	s_nop 0
	global_load_lds_dwordx4 v198, s[68:69]
	s_add_u32 m0, s76, 0x1e000
	s_nop 0
	global_load_lds_dwordx4 v199, s[68:69]
	s_add_u32 m0, s76, 0x20000
	s_nop 0
	global_load_lds_dwordx4 v196, s[70:71]
	s_add_u32 m0, s76, 0x22000
	s_nop 0
	global_load_lds_dwordx4 v197, s[70:71]
	s_add_u32 s68, s68, 0x80
	s_addc_u32 s69, s69, 0
	s_add_u32 s70, s70, 0x80
	s_addc_u32 s71, s71, 0
	s_waitcnt lgkmcnt(0)
	v_add_u32_e32 v204, 0x0, v201
	v_add_u32_e32 v205, 0x0, v203
	ds_read_b128 v[212:215], v204 offset:0
	ds_read_b128 v[216:219], v204 offset:2048
	ds_read_b128 v[220:223], v204 offset:4096
	ds_read_b128 v[224:227], v204 offset:6144
	ds_read_b128 v[228:231], v205 offset:0
	ds_read_b128 v[232:235], v205 offset:2048
	ds_read_b128 v[236:239], v205 offset:4096
	ds_read_b128 v[240:243], v205 offset:6144
	v_mfma_f32_16x16x32_bf16 v[2:5], v[146:149], v[130:133], 0
	v_mfma_f32_16x16x32_bf16 v[6:9], v[150:153], v[130:133], 0
	global_load_dwordx4 v[174:177], v190, s[72:73] offset:0
	v_mfma_f32_16x16x32_bf16 v[10:13], v[154:157], v[130:133], 0
	v_mfma_f32_16x16x32_bf16 v[14:17], v[158:161], v[130:133], 0
	global_load_dwordx4 v[178:181], v190, s[72:73] offset:64
	v_mfma_f32_16x16x32_bf16 v[18:21], v[146:149], v[134:137], 0
	v_mfma_f32_16x16x32_bf16 v[22:25], v[150:153], v[134:137], 0
	global_load_dwordx4 v[182:185], v190, s[72:73] offset:128
	v_mfma_f32_16x16x32_bf16 v[26:29], v[154:157], v[134:137], 0
	v_mfma_f32_16x16x32_bf16 v[30:33], v[158:161], v[134:137], 0
	global_load_dwordx4 v[186:189], v190, s[72:73] offset:192
	v_mfma_f32_16x16x32_bf16 v[34:37], v[146:149], v[138:141], 0
	v_mfma_f32_16x16x32_bf16 v[38:41], v[150:153], v[138:141], 0
	global_load_dwordx2 v[66:67], v206, s[74:75] offset:0
	v_mfma_f32_16x16x32_bf16 v[42:45], v[154:157], v[138:141], 0
	v_mfma_f32_16x16x32_bf16 v[46:49], v[158:161], v[138:141], 0
	global_load_dwordx2 v[70:71], v206, s[74:75] offset:32
	v_mfma_f32_16x16x32_bf16 v[50:53], v[146:149], v[142:145], 0
	v_mfma_f32_16x16x32_bf16 v[54:57], v[150:153], v[142:145], 0
	global_load_dwordx2 v[74:75], v206, s[74:75] offset:64
	v_mfma_f32_16x16x32_bf16 v[58:61], v[154:157], v[142:145], 0
	v_mfma_f32_16x16x32_bf16 v[62:65], v[158:161], v[142:145], 0
	s_waitcnt vmcnt(13)
	s_waitcnt lgkmcnt(0)
	s_barrier
	v_add_u32_e32 v204, 0xc000, v200
	v_add_u32_e32 v205, 0xc000, v202
	ds_read_b128 v[130:133], v204 offset:0
	ds_read_b128 v[134:137], v204 offset:2048
	ds_read_b128 v[138:141], v204 offset:4096
	ds_read_b128 v[142:145], v204 offset:6144
	ds_read_b128 v[146:149], v205 offset:0
	ds_read_b128 v[150:153], v205 offset:2048
	ds_read_b128 v[154:157], v205 offset:4096
	ds_read_b128 v[158:161], v205 offset:6144
	v_mfma_f32_16x16x32_bf16 v[2:5], v[228:231], v[212:215], v[2:5]
	v_mfma_f32_16x16x32_bf16 v[6:9], v[232:235], v[212:215], v[6:9]
	s_add_u32 m0, s76, 0x0
	s_nop 0
	global_load_lds_dwordx4 v196, s[68:69]
	v_mfma_f32_16x16x32_bf16 v[10:13], v[236:239], v[212:215], v[10:13]
	v_mfma_f32_16x16x32_bf16 v[14:17], v[240:243], v[212:215], v[14:17]
	s_add_u32 m0, s76, 0x2000
	s_nop 0
	global_load_lds_dwordx4 v197, s[68:69]
	v_mfma_f32_16x16x32_bf16 v[18:21], v[228:231], v[216:219], v[18:21]
	v_mfma_f32_16x16x32_bf16 v[22:25], v[232:235], v[216:219], v[22:25]
	s_add_u32 m0, s76, 0x4000
	s_nop 0
	global_load_lds_dwordx4 v198, s[68:69]
	v_mfma_f32_16x16x32_bf16 v[26:29], v[236:239], v[216:219], v[26:29]
	v_mfma_f32_16x16x32_bf16 v[30:33], v[240:243], v[216:219], v[30:33]
	s_add_u32 m0, s76, 0x6000
	s_nop 0
	global_load_lds_dwordx4 v199, s[68:69]
	v_mfma_f32_16x16x32_bf16 v[34:37], v[228:231], v[220:223], v[34:37]
	v_mfma_f32_16x16x32_bf16 v[38:41], v[232:235], v[220:223], v[38:41]
	s_add_u32 m0, s76, 0x8000
	s_nop 0
	global_load_lds_dwordx4 v196, s[70:71]
	v_mfma_f32_16x16x32_bf16 v[42:45], v[236:239], v[220:223], v[42:45]
	v_mfma_f32_16x16x32_bf16 v[46:49], v[240:243], v[220:223], v[46:49]
	s_add_u32 m0, s76, 0xa000
	s_nop 0
	global_load_lds_dwordx4 v197, s[70:71]
	v_mfma_f32_16x16x32_bf16 v[50:53], v[228:231], v[224:227], v[50:53]
	v_mfma_f32_16x16x32_bf16 v[54:57], v[232:235], v[224:227], v[54:57]
	s_add_u32 s68, s68, 0x80
	s_addc_u32 s69, s69, 0
	s_add_u32 s70, s70, 0x80
	s_addc_u32 s71, s71, 0
	v_mfma_f32_16x16x32_bf16 v[58:61], v[236:239], v[224:227], v[58:61]
	v_mfma_f32_16x16x32_bf16 v[62:65], v[240:243], v[224:227], v[62:65]
	s_waitcnt lgkmcnt(0)
	v_add_u32_e32 v204, 0xc000, v201
	v_add_u32_e32 v205, 0xc000, v203
	ds_read_b128 v[212:215], v204 offset:0
	ds_read_b128 v[216:219], v204 offset:2048
	ds_read_b128 v[220:223], v204 offset:4096
	ds_read_b128 v[224:227], v204 offset:6144
	ds_read_b128 v[228:231], v205 offset:0
	ds_read_b128 v[232:235], v205 offset:2048
	ds_read_b128 v[236:239], v205 offset:4096
	ds_read_b128 v[240:243], v205 offset:6144
	v_mfma_f32_16x16x32_bf16 v[2:5], v[146:149], v[130:133], v[2:5]
	v_mfma_f32_16x16x32_bf16 v[6:9], v[150:153], v[130:133], v[6:9]
	global_load_dwordx2 v[78:79], v206, s[74:75] offset:96
	v_mfma_f32_16x16x32_bf16 v[10:13], v[154:157], v[130:133], v[10:13]
	v_mfma_f32_16x16x32_bf16 v[14:17], v[158:161], v[130:133], v[14:17]
	global_load_dwordx2 v[82:83], v207, s[74:75] offset:0
	v_mfma_f32_16x16x32_bf16 v[18:21], v[146:149], v[134:137], v[18:21]
	v_mfma_f32_16x16x32_bf16 v[22:25], v[150:153], v[134:137], v[22:25]
	global_load_dwordx2 v[86:87], v207, s[74:75] offset:32
	v_mfma_f32_16x16x32_bf16 v[26:29], v[154:157], v[134:137], v[26:29]
	v_mfma_f32_16x16x32_bf16 v[30:33], v[158:161], v[134:137], v[30:33]
	global_load_dwordx2 v[90:91], v207, s[74:75] offset:64
	v_mfma_f32_16x16x32_bf16 v[34:37], v[146:149], v[138:141], v[34:37]
	v_mfma_f32_16x16x32_bf16 v[38:41], v[150:153], v[138:141], v[38:41]
	global_load_dwordx2 v[94:95], v207, s[74:75] offset:96
	v_mfma_f32_16x16x32_bf16 v[42:45], v[154:157], v[138:141], v[42:45]
	v_mfma_f32_16x16x32_bf16 v[46:49], v[158:161], v[138:141], v[46:49]
	global_load_dwordx2 v[98:99], v208, s[74:75] offset:0
	v_mfma_f32_16x16x32_bf16 v[50:53], v[146:149], v[142:145], v[50:53]
	v_mfma_f32_16x16x32_bf16 v[54:57], v[150:153], v[142:145], v[54:57]
	global_load_dwordx2 v[102:103], v208, s[74:75] offset:32
	v_mfma_f32_16x16x32_bf16 v[58:61], v[154:157], v[142:145], v[58:61]
	v_mfma_f32_16x16x32_bf16 v[62:65], v[158:161], v[142:145], v[62:65]
	s_waitcnt vmcnt(20)
	s_waitcnt lgkmcnt(0)
	s_barrier
	v_add_u32_e32 v204, 0x18000, v200
	v_add_u32_e32 v205, 0x18000, v202
	ds_read_b128 v[130:133], v204 offset:0
	ds_read_b128 v[134:137], v204 offset:2048
	ds_read_b128 v[138:141], v204 offset:4096
	ds_read_b128 v[142:145], v204 offset:6144
	ds_read_b128 v[146:149], v205 offset:0
	ds_read_b128 v[150:153], v205 offset:2048
	ds_read_b128 v[154:157], v205 offset:4096
	ds_read_b128 v[158:161], v205 offset:6144
	v_mfma_f32_16x16x32_bf16 v[2:5], v[228:231], v[212:215], v[2:5]
	v_mfma_f32_16x16x32_bf16 v[6:9], v[232:235], v[212:215], v[6:9]
	s_add_u32 m0, s76, 0xc000
	s_nop 0
	global_load_lds_dwordx4 v196, s[68:69]
	v_mfma_f32_16x16x32_bf16 v[10:13], v[236:239], v[212:215], v[10:13]
	v_mfma_f32_16x16x32_bf16 v[14:17], v[240:243], v[212:215], v[14:17]
	s_add_u32 m0, s76, 0xe000
	s_nop 0
	global_load_lds_dwordx4 v197, s[68:69]
	v_mfma_f32_16x16x32_bf16 v[18:21], v[228:231], v[216:219], v[18:21]
	v_mfma_f32_16x16x32_bf16 v[22:25], v[232:235], v[216:219], v[22:25]
	s_add_u32 m0, s76, 0x10000
	s_nop 0
	global_load_lds_dwordx4 v198, s[68:69]
	v_mfma_f32_16x16x32_bf16 v[26:29], v[236:239], v[216:219], v[26:29]
	v_mfma_f32_16x16x32_bf16 v[30:33], v[240:243], v[216:219], v[30:33]
	s_add_u32 m0, s76, 0x12000
	s_nop 0
	global_load_lds_dwordx4 v199, s[68:69]
	v_mfma_f32_16x16x32_bf16 v[34:37], v[228:231], v[220:223], v[34:37]
	v_mfma_f32_16x16x32_bf16 v[38:41], v[232:235], v[220:223], v[38:41]
	s_add_u32 m0, s76, 0x14000
	s_nop 0
	global_load_lds_dwordx4 v196, s[70:71]
	v_mfma_f32_16x16x32_bf16 v[42:45], v[236:239], v[220:223], v[42:45]
	v_mfma_f32_16x16x32_bf16 v[46:49], v[240:243], v[220:223], v[46:49]
	s_add_u32 m0, s76, 0x16000
	s_nop 0
	global_load_lds_dwordx4 v197, s[70:71]
	v_mfma_f32_16x16x32_bf16 v[50:53], v[228:231], v[224:227], v[50:53]
	v_mfma_f32_16x16x32_bf16 v[54:57], v[232:235], v[224:227], v[54:57]
	s_add_u32 s68, s68, 0x80
	s_addc_u32 s69, s69, 0
	s_add_u32 s70, s70, 0x80
	s_addc_u32 s71, s71, 0
	v_mfma_f32_16x16x32_bf16 v[58:61], v[236:239], v[224:227], v[58:61]
	v_mfma_f32_16x16x32_bf16 v[62:65], v[240:243], v[224:227], v[62:65]
	s_waitcnt lgkmcnt(0)
	v_add_u32_e32 v204, 0x18000, v201
	v_add_u32_e32 v205, 0x18000, v203
	ds_read_b128 v[212:215], v204 offset:0
	ds_read_b128 v[216:219], v204 offset:2048
	ds_read_b128 v[220:223], v204 offset:4096
	ds_read_b128 v[224:227], v204 offset:6144
	ds_read_b128 v[228:231], v205 offset:0
	ds_read_b128 v[232:235], v205 offset:2048
	ds_read_b128 v[236:239], v205 offset:4096
	ds_read_b128 v[240:243], v205 offset:6144
	v_mfma_f32_16x16x32_bf16 v[2:5], v[146:149], v[130:133], v[2:5]
	v_mfma_f32_16x16x32_bf16 v[6:9], v[150:153], v[130:133], v[6:9]
	global_load_dwordx2 v[106:107], v208, s[74:75] offset:64
	v_mfma_f32_16x16x32_bf16 v[10:13], v[154:157], v[130:133], v[10:13]
	v_mfma_f32_16x16x32_bf16 v[14:17], v[158:161], v[130:133], v[14:17]
	global_load_dwordx2 v[110:111], v208, s[74:75] offset:96
	v_mfma_f32_16x16x32_bf16 v[18:21], v[146:149], v[134:137], v[18:21]
	v_mfma_f32_16x16x32_bf16 v[22:25], v[150:153], v[134:137], v[22:25]
	global_load_dwordx2 v[114:115], v209, s[74:75] offset:0
	v_mfma_f32_16x16x32_bf16 v[26:29], v[154:157], v[134:137], v[26:29]
	v_mfma_f32_16x16x32_bf16 v[30:33], v[158:161], v[134:137], v[30:33]
	global_load_dwordx2 v[118:119], v209, s[74:75] offset:32
	v_mfma_f32_16x16x32_bf16 v[34:37], v[146:149], v[138:141], v[34:37]
	v_mfma_f32_16x16x32_bf16 v[38:41], v[150:153], v[138:141], v[38:41]
	global_load_dwordx2 v[122:123], v209, s[74:75] offset:64
	v_mfma_f32_16x16x32_bf16 v[42:45], v[154:157], v[138:141], v[42:45]
	v_mfma_f32_16x16x32_bf16 v[46:49], v[158:161], v[138:141], v[46:49]
	global_load_dwordx2 v[126:127], v209, s[74:75] offset:96
	v_mfma_f32_16x16x32_bf16 v[50:53], v[146:149], v[142:145], v[50:53]
	v_mfma_f32_16x16x32_bf16 v[54:57], v[150:153], v[142:145], v[54:57]
	v_mfma_f32_16x16x32_bf16 v[58:61], v[154:157], v[142:145], v[58:61]
	v_mfma_f32_16x16x32_bf16 v[62:65], v[158:161], v[142:145], v[62:65]
	s_waitcnt vmcnt(19)
	s_waitcnt lgkmcnt(0)
	s_barrier
	v_add_u32_e32 v204, 0x0, v200
	v_add_u32_e32 v205, 0x0, v202
	ds_read_b128 v[130:133], v204 offset:0
	ds_read_b128 v[134:137], v204 offset:2048
	ds_read_b128 v[138:141], v204 offset:4096
	ds_read_b128 v[142:145], v204 offset:6144
	ds_read_b128 v[146:149], v205 offset:0
	ds_read_b128 v[150:153], v205 offset:2048
	ds_read_b128 v[154:157], v205 offset:4096
	ds_read_b128 v[158:161], v205 offset:6144
	v_mfma_f32_16x16x32_bf16 v[2:5], v[228:231], v[212:215], v[2:5]
	v_mfma_f32_16x16x32_bf16 v[6:9], v[232:235], v[212:215], v[6:9]
	s_add_u32 m0, s76, 0x18000
	s_nop 0
	global_load_lds_dwordx4 v196, s[68:69]
	v_mfma_f32_16x16x32_bf16 v[10:13], v[236:239], v[212:215], v[10:13]
	v_mfma_f32_16x16x32_bf16 v[14:17], v[240:243], v[212:215], v[14:17]
	s_add_u32 m0, s76, 0x1a000
	s_nop 0
	global_load_lds_dwordx4 v197, s[68:69]
	v_mfma_f32_16x16x32_bf16 v[18:21], v[228:231], v[216:219], v[18:21]
	v_mfma_f32_16x16x32_bf16 v[22:25], v[232:235], v[216:219], v[22:25]
	s_add_u32 m0, s76, 0x1c000
	s_nop 0
	global_load_lds_dwordx4 v198, s[68:69]
	v_mfma_f32_16x16x32_bf16 v[26:29], v[236:239], v[216:219], v[26:29]
	v_mfma_f32_16x16x32_bf16 v[30:33], v[240:243], v[216:219], v[30:33]
	s_add_u32 m0, s76, 0x1e000
	s_nop 0
	global_load_lds_dwordx4 v199, s[68:69]
	v_mfma_f32_16x16x32_bf16 v[34:37], v[228:231], v[220:223], v[34:37]
	v_mfma_f32_16x16x32_bf16 v[38:41], v[232:235], v[220:223], v[38:41]
	s_add_u32 m0, s76, 0x20000
	s_nop 0
	global_load_lds_dwordx4 v196, s[70:71]
	v_mfma_f32_16x16x32_bf16 v[42:45], v[236:239], v[220:223], v[42:45]
	v_mfma_f32_16x16x32_bf16 v[46:49], v[240:243], v[220:223], v[46:49]
	s_add_u32 m0, s76, 0x22000
	s_nop 0
	global_load_lds_dwordx4 v197, s[70:71]
	v_mfma_f32_16x16x32_bf16 v[50:53], v[228:231], v[224:227], v[50:53]
	v_mfma_f32_16x16x32_bf16 v[54:57], v[232:235], v[224:227], v[54:57]
	s_add_u32 s68, s68, 0x80
	s_addc_u32 s69, s69, 0
	s_add_u32 s70, s70, 0x80
	s_addc_u32 s71, s71, 0
	v_mfma_f32_16x16x32_bf16 v[58:61], v[236:239], v[224:227], v[58:61]
	v_mfma_f32_16x16x32_bf16 v[62:65], v[240:243], v[224:227], v[62:65]
	s_waitcnt lgkmcnt(0)
	v_add_u32_e32 v204, 0x0, v201
	v_add_u32_e32 v205, 0x0, v203
	ds_read_b128 v[212:215], v204 offset:0
	ds_read_b128 v[216:219], v204 offset:2048
	ds_read_b128 v[220:223], v204 offset:4096
	ds_read_b128 v[224:227], v204 offset:6144
	ds_read_b128 v[228:231], v205 offset:0
	ds_read_b128 v[232:235], v205 offset:2048
	ds_read_b128 v[236:239], v205 offset:4096
	ds_read_b128 v[240:243], v205 offset:6144
	v_mfma_f32_16x16x32_bf16 v[2:5], v[146:149], v[130:133], v[2:5]
	v_mfma_f32_16x16x32_bf16 v[6:9], v[150:153], v[130:133], v[6:9]
	v_mfma_f32_16x16x32_bf16 v[10:13], v[154:157], v[130:133], v[10:13]
	v_mfma_f32_16x16x32_bf16 v[14:17], v[158:161], v[130:133], v[14:17]
	v_mfma_f32_16x16x32_bf16 v[18:21], v[146:149], v[134:137], v[18:21]
	v_mfma_f32_16x16x32_bf16 v[22:25], v[150:153], v[134:137], v[22:25]
	v_mfma_f32_16x16x32_bf16 v[26:29], v[154:157], v[134:137], v[26:29]
	v_mfma_f32_16x16x32_bf16 v[30:33], v[158:161], v[134:137], v[30:33]
	v_mfma_f32_16x16x32_bf16 v[34:37], v[146:149], v[138:141], v[34:37]
	v_mfma_f32_16x16x32_bf16 v[38:41], v[150:153], v[138:141], v[38:41]
	v_mfma_f32_16x16x32_bf16 v[42:45], v[154:157], v[138:141], v[42:45]
	v_mfma_f32_16x16x32_bf16 v[46:49], v[158:161], v[138:141], v[46:49]
	v_mfma_f32_16x16x32_bf16 v[50:53], v[146:149], v[142:145], v[50:53]
	v_mfma_f32_16x16x32_bf16 v[54:57], v[150:153], v[142:145], v[54:57]
	v_mfma_f32_16x16x32_bf16 v[58:61], v[154:157], v[142:145], v[58:61]
	v_mfma_f32_16x16x32_bf16 v[62:65], v[158:161], v[142:145], v[62:65]
	s_waitcnt vmcnt(12)
	s_waitcnt lgkmcnt(0)
	s_barrier
	v_add_u32_e32 v204, 0xc000, v200
	v_add_u32_e32 v205, 0xc000, v202
	ds_read_b128 v[130:133], v204 offset:0
	ds_read_b128 v[134:137], v204 offset:2048
	ds_read_b128 v[138:141], v204 offset:4096
	ds_read_b128 v[142:145], v204 offset:6144
	ds_read_b128 v[146:149], v205 offset:0
	ds_read_b128 v[150:153], v205 offset:2048
	ds_read_b128 v[154:157], v205 offset:4096
	ds_read_b128 v[158:161], v205 offset:6144
	v_mfma_f32_16x16x32_bf16 v[2:5], v[228:231], v[212:215], v[2:5]
	v_mfma_f32_16x16x32_bf16 v[6:9], v[232:235], v[212:215], v[6:9]
	s_add_u32 m0, s76, 0x0
	s_nop 0
	global_load_lds_dwordx4 v196, s[68:69]
	v_mfma_f32_16x16x32_bf16 v[10:13], v[236:239], v[212:215], v[10:13]
	v_mfma_f32_16x16x32_bf16 v[14:17], v[240:243], v[212:215], v[14:17]
	s_add_u32 m0, s76, 0x2000
	s_nop 0
	global_load_lds_dwordx4 v197, s[68:69]
	v_mfma_f32_16x16x32_bf16 v[18:21], v[228:231], v[216:219], v[18:21]
	v_mfma_f32_16x16x32_bf16 v[22:25], v[232:235], v[216:219], v[22:25]
	s_add_u32 m0, s76, 0x4000
	s_nop 0
	global_load_lds_dwordx4 v198, s[68:69]
	v_mfma_f32_16x16x32_bf16 v[26:29], v[236:239], v[216:219], v[26:29]
	v_mfma_f32_16x16x32_bf16 v[30:33], v[240:243], v[216:219], v[30:33]
	s_add_u32 m0, s76, 0x6000
	s_nop 0
	global_load_lds_dwordx4 v199, s[68:69]
	v_mfma_f32_16x16x32_bf16 v[34:37], v[228:231], v[220:223], v[34:37]
	v_mfma_f32_16x16x32_bf16 v[38:41], v[232:235], v[220:223], v[38:41]
	s_add_u32 m0, s76, 0x8000
	s_nop 0
	global_load_lds_dwordx4 v196, s[70:71]
	v_mfma_f32_16x16x32_bf16 v[42:45], v[236:239], v[220:223], v[42:45]
	v_mfma_f32_16x16x32_bf16 v[46:49], v[240:243], v[220:223], v[46:49]
	s_add_u32 m0, s76, 0xa000
	s_nop 0
	global_load_lds_dwordx4 v197, s[70:71]
	v_mfma_f32_16x16x32_bf16 v[50:53], v[228:231], v[224:227], v[50:53]
	v_mfma_f32_16x16x32_bf16 v[54:57], v[232:235], v[224:227], v[54:57]
	s_add_u32 s68, s68, 0x80
	s_addc_u32 s69, s69, 0
	s_add_u32 s70, s70, 0x80
	s_addc_u32 s71, s71, 0
	v_mfma_f32_16x16x32_bf16 v[58:61], v[236:239], v[224:227], v[58:61]
	v_mfma_f32_16x16x32_bf16 v[62:65], v[240:243], v[224:227], v[62:65]
	s_waitcnt lgkmcnt(0)
	v_add_u32_e32 v204, 0xc000, v201
	v_add_u32_e32 v205, 0xc000, v203
	ds_read_b128 v[212:215], v204 offset:0
	ds_read_b128 v[216:219], v204 offset:2048
	ds_read_b128 v[220:223], v204 offset:4096
	ds_read_b128 v[224:227], v204 offset:6144
	ds_read_b128 v[228:231], v205 offset:0
	ds_read_b128 v[232:235], v205 offset:2048
	ds_read_b128 v[236:239], v205 offset:4096
	ds_read_b128 v[240:243], v205 offset:6144
	v_mfma_f32_16x16x32_bf16 v[2:5], v[146:149], v[130:133], v[2:5]
	v_mfma_f32_16x16x32_bf16 v[6:9], v[150:153], v[130:133], v[6:9]
	v_mfma_f32_16x16x32_bf16 v[10:13], v[154:157], v[130:133], v[10:13]
	v_mfma_f32_16x16x32_bf16 v[14:17], v[158:161], v[130:133], v[14:17]
	v_mfma_f32_16x16x32_bf16 v[18:21], v[146:149], v[134:137], v[18:21]
	v_mfma_f32_16x16x32_bf16 v[22:25], v[150:153], v[134:137], v[22:25]
	v_mfma_f32_16x16x32_bf16 v[26:29], v[154:157], v[134:137], v[26:29]
	v_mfma_f32_16x16x32_bf16 v[30:33], v[158:161], v[134:137], v[30:33]
	v_mfma_f32_16x16x32_bf16 v[34:37], v[146:149], v[138:141], v[34:37]
	v_mfma_f32_16x16x32_bf16 v[38:41], v[150:153], v[138:141], v[38:41]
	v_mfma_f32_16x16x32_bf16 v[42:45], v[154:157], v[138:141], v[42:45]
	v_mfma_f32_16x16x32_bf16 v[46:49], v[158:161], v[138:141], v[46:49]
	v_mfma_f32_16x16x32_bf16 v[50:53], v[146:149], v[142:145], v[50:53]
	v_mfma_f32_16x16x32_bf16 v[54:57], v[150:153], v[142:145], v[54:57]
	v_mfma_f32_16x16x32_bf16 v[58:61], v[154:157], v[142:145], v[58:61]
	v_mfma_f32_16x16x32_bf16 v[62:65], v[158:161], v[142:145], v[62:65]
	s_mov_b32 s16, 12

.LBB0_746:
	s_or_b64 exec, exec, s[4:5]
	s_waitcnt vmcnt(0)
	v_readfirstlane_b32 s4, v5
	v_sub_u32_e32 v6, 0, v4
	s_nop 0
	v_add_u32_e32 v5, s4, v3
	v_cvt_f32_u32_e32 v3, v4
	v_rcp_iflag_f32_e32 v3, v3
	s_nop 0
	v_mul_f32_e32 v3, 0x4f7ffffe, v3
	v_cvt_u32_f32_e32 v3, v3
	v_mul_lo_u32 v6, v6, v3
	v_mul_hi_u32 v6, v3, v6
	v_add_u32_e32 v3, v3, v6
	v_mul_hi_u32 v3, v5, v3
	v_mul_lo_u32 v6, v3, v4
	v_sub_u32_e32 v6, v5, v6
	v_cmp_ge_u32_e32 vcc, v6, v4
	v_add_u32_e32 v7, 1, v3
	s_nop 0
	v_cndmask_b32_e32 v3, v3, v7, vcc
	v_sub_u32_e32 v7, v6, v4
	v_cndmask_b32_e32 v6, v6, v7, vcc
	v_cmp_ge_u32_e32 vcc, v6, v4
	v_add_u32_e32 v6, 1, v3
	s_nop 0
	v_cndmask_b32_e32 v3, v3, v6, vcc
	v_add_u32_e32 v6, 1, v5
	v_mad_u64_u32 v[4:5], s[4:5], v4, v3, v[4:5]
	v_cmp_ne_u32_e32 vcc, v6, v4
	s_and_saveexec_b64 s[4:5], vcc
	s_xor_b64 s[4:5], exec, s[4:5]
	s_cbranch_execz .LBB0_760
	v_readlane_b32 s6, v253, 46
	v_readlane_b32 s7, v253, 47
	s_nop 4
	v_mad_u32_u24 v6, v3, v2, v2
	global_load_dword v2, v163, s[6:7] sc1
	s_waitcnt vmcnt(0)
	v_cmp_lt_u32_e32 vcc, v2, v6
	s_and_saveexec_b64 s[6:7], vcc
	s_cbranch_execz .LBB0_759
	s_mov_b32 s19, 1
	s_mov_b64 s[8:9], 0
	s_branch .LBB0_750

.LBB0_777:
	s_or_b64 exec, exec, s[4:5]
	s_mov_b64 s[4:5], exec
	v_mbcnt_lo_u32_b32 v2, s4, 0
	v_mbcnt_hi_u32_b32 v2, s5, v2
	v_cmp_eq_u32_e32 vcc, 0, v2
	s_waitcnt vmcnt(0)
	buffer_inv sc1
	s_and_saveexec_b64 s[6:7], vcc
	s_cbranch_execz .LBB0_779
	s_bcnt1_i32_b64 s4, s[4:5]
	v_mov_b32_e32 v2, s4
	v_readlane_b32 s4, v253, 44
	v_readlane_b32 s5, v253, 45
	s_nop 4
.LBB0_779:
	s_or_b64 exec, exec, s[6:7]
	s_waitcnt vmcnt(0)
